# ATTN ping-pong, COMPUTE segment re-spaced by issue cost (3 exp2 per MFMA gap, packs behind the row-sum MFMA)
# baseline (speedup 1.0000x reference)
.LBB0_955:
	s_add_i32 s35, s15, -2
	s_lshl_b32 s5, s34, 13
	s_cmp_lt_u32 s15, s27
	s_cselect_b32 s10, s15, s29
	s_lshl_b64 s[6:7], s[10:11], 16
	s_waitcnt vmcnt(0)
	v_lshrrev_b32_e32 v3, v1, v138
	v_lshl_add_u64 v[6:7], v[116:117], 0, s[6:7]
	v_lshl_add_u64 v[8:9], v[118:119], 0, s[6:7]
	s_add_i32 s6, s5, 0xffffe000
	v_lshlrev_b32_e32 v3, 4, v3
	s_cmp_lg_u32 s34, 0
	v_and_b32_e32 v4, 0xf0f0f0f0, v3
	v_lshrrev_b32_e32 v3, v1, v139
	s_cselect_b32 s6, s6, 0x4000
	v_lshlrev_b32_e32 v3, 4, v3
	s_add_i32 s6, s6, 0
	v_and_b32_e32 v3, 0xf0f0f0f0, v3
	s_add_i32 s6, s20, s6
	s_waitcnt lgkmcnt(0)
	s_barrier
	s_add_i32 s7, s6, 0x6000
	s_mov_b32 m0, s6
	global_load_lds_dwordx4 v[6:7], off
	s_mov_b32 m0, s7
	global_load_lds_dwordx4 v[8:9], off
	s_add_i32 s6, s15, -1
	s_cmp_lt_u32 s35, 63
	s_cselect_b32 s10, s6, 63
	s_lshl_b64 s[6:7], s[10:11], 15
	v_lshl_add_u64 v[6:7], v[136:137], 0, s[6:7]
	global_load_dwordx2 v[138:139], v[6:7], off
	s_cmp_gt_u32 s35, s28
	s_cbranch_scc1 .Lpp_skip
	v_add_u32_e32 v149, s5, v140
	v_add_u32_e32 v150, s5, v141
	v_add_u32_sdwa v230, v4, s25 dst_sel:DWORD dst_unused:UNUSED_PAD src0_sel:BYTE_0 src1_sel:DWORD
	v_add_u32_sdwa v231, v4, s25 dst_sel:DWORD dst_unused:UNUSED_PAD src0_sel:BYTE_1 src1_sel:DWORD
	v_add_u32_sdwa v232, v4, s25 dst_sel:DWORD dst_unused:UNUSED_PAD src0_sel:BYTE_2 src1_sel:DWORD
	v_add_u32_sdwa v233, v4, s25 dst_sel:DWORD dst_unused:UNUSED_PAD src0_sel:BYTE_3 src1_sel:DWORD
	v_add_u32_sdwa v234, v3, s25 dst_sel:DWORD dst_unused:UNUSED_PAD src0_sel:BYTE_0 src1_sel:DWORD
	v_add_u32_sdwa v235, v3, s25 dst_sel:DWORD dst_unused:UNUSED_PAD src0_sel:BYTE_1 src1_sel:DWORD
	v_add_u32_sdwa v236, v3, s25 dst_sel:DWORD dst_unused:UNUSED_PAD src0_sel:BYTE_2 src1_sel:DWORD
	v_add_u32_sdwa v237, v3, s25 dst_sel:DWORD dst_unused:UNUSED_PAD src0_sel:BYTE_3 src1_sel:DWORD
	ds_read_b128 v[66:69], v230
	ds_read_b128 v[70:73], v231
	ds_read_b128 v[74:77], v232
	ds_read_b128 v[78:81], v233
	ds_read_b128 v[182:185], v149
	ds_read_b128 v[186:189], v149 offset:2048
	ds_read_b128 v[190:193], v149 offset:4096
	ds_read_b128 v[194:197], v149 offset:6144
	ds_read_b128 v[82:85], v234
	ds_read_b128 v[86:89], v235
	ds_read_b128 v[90:93], v236
	ds_read_b128 v[94:97], v237
	s_waitcnt lgkmcnt(8)
	ds_read_b128 v[198:201], v149 offset:512
	ds_read_b128 v[202:205], v149 offset:2560
	ds_read_b128 v[206:209], v149 offset:4608
	ds_read_b128 v[210:213], v149 offset:6656
	s_waitcnt lgkmcnt(8)
	ds_read_b64_tr_b16 v[152:153], v150
	ds_read_b64_tr_b16 v[154:155], v150 offset:512
	ds_read_b64_tr_b16 v[156:157], v150 offset:1024
	ds_read_b64_tr_b16 v[158:159], v150 offset:1536
	s_waitcnt lgkmcnt(8)
	ds_read_b64_tr_b16 v[160:161], v150 offset:2048
	ds_read_b64_tr_b16 v[162:163], v150 offset:2560
	ds_read_b64_tr_b16 v[164:165], v150 offset:3072
	ds_read_b64_tr_b16 v[166:167], v150 offset:3584
	s_waitcnt lgkmcnt(8)
	ds_read_b64_tr_b16 v[168:169], v150 offset:4096
	ds_read_b64_tr_b16 v[170:171], v150 offset:4608
	ds_read_b64_tr_b16 v[172:173], v150 offset:5120
	ds_read_b64_tr_b16 v[174:175], v150 offset:5632
	s_waitcnt lgkmcnt(8)
	ds_read_b64_tr_b16 v[214:215], v150 offset:6144
	ds_read_b64_tr_b16 v[216:217], v150 offset:6656
	ds_read_b64_tr_b16 v[218:219], v150 offset:7168
	ds_read_b64_tr_b16 v[220:221], v150 offset:7680
	s_waitcnt lgkmcnt(0)
	s_barrier
	v_mfma_f32_32x32x16_bf16 v[66:81], v[182:185], v[110:113], v[66:81]
	v_mfma_f32_32x32x16_bf16 v[66:81], v[186:189], v[98:101], v[66:81]
	v_mfma_f32_32x32x16_bf16 v[66:81], v[190:193], v[102:105], v[66:81]
	v_mfma_f32_32x32x16_bf16 v[66:81], v[194:197], v[106:109], v[66:81]
	s_cmp_lt_u32 s33, s14
	s_cbranch_scc0 .Lpp_bias
	v_mfma_f32_32x32x16_bf16 v[82:97], v[198:201], v[110:113], v[82:97]
	s_nop 5
	v_mfma_f32_32x32x16_bf16 v[82:97], v[202:205], v[98:101], v[82:97]
	s_nop 3
	v_exp_f32_e32 v66, v66
	v_mfma_f32_32x32x16_bf16 v[82:97], v[206:209], v[102:105], v[82:97]
	v_exp_f32_e32 v67, v67
	v_exp_f32_e32 v68, v68
	v_exp_f32_e32 v69, v69
	v_mfma_f32_32x32x16_bf16 v[82:97], v[210:213], v[106:109], v[82:97]
	v_exp_f32_e32 v70, v70
	v_exp_f32_e32 v71, v71
	v_exp_f32_e32 v72, v72
	v_exp_f32_e32 v73, v73
	v_cvt_pk_bf16_f32 v4, v66, v67
	v_cvt_pk_bf16_f32 v5, v68, v69
	v_cvt_pk_bf16_f32 v6, v70, v71
	v_cvt_pk_bf16_f32 v7, v72, v73
	s_nop 1
	v_mfma_f32_32x32x16_bf16 v[34:49], v[4:7], v[152:155], v[34:49]
	v_exp_f32_e32 v74, v74
	v_exp_f32_e32 v75, v75
	v_exp_f32_e32 v76, v76
	v_mfma_f32_32x32x16_bf16 v[18:33], v[4:7], v[168:171], v[18:33]
	v_exp_f32_e32 v77, v77
	v_exp_f32_e32 v78, v78
	v_exp_f32_e32 v79, v79
	v_mfma_f32_32x32x16_bf16 v[50:65], v[4:7], v[226:229], v[50:65]
	v_exp_f32_e32 v80, v80
	v_exp_f32_e32 v81, v81
	v_cvt_pk_bf16_f32 v8, v74, v75
	v_cvt_pk_bf16_f32 v9, v76, v77
	v_cvt_pk_bf16_f32 v10, v78, v79
	v_cvt_pk_bf16_f32 v11, v80, v81
	s_nop 1
	v_mfma_f32_32x32x16_bf16 v[34:49], v[8:11], v[156:159], v[34:49]
	v_exp_f32_e32 v82, v82
	v_exp_f32_e32 v83, v83
	v_exp_f32_e32 v84, v84
	v_mfma_f32_32x32x16_bf16 v[18:33], v[8:11], v[172:175], v[18:33]
	v_exp_f32_e32 v85, v85
	v_exp_f32_e32 v86, v86
	v_exp_f32_e32 v87, v87
	v_mfma_f32_32x32x16_bf16 v[50:65], v[8:11], v[226:229], v[50:65]
	v_exp_f32_e32 v88, v88
	v_exp_f32_e32 v89, v89
	v_cvt_pk_bf16_f32 v12, v82, v83
	v_cvt_pk_bf16_f32 v13, v84, v85
	v_cvt_pk_bf16_f32 v14, v86, v87
	v_cvt_pk_bf16_f32 v15, v88, v89
	s_nop 1
	v_mfma_f32_32x32x16_bf16 v[34:49], v[12:15], v[160:163], v[34:49]
	v_exp_f32_e32 v90, v90
	v_exp_f32_e32 v91, v91
	v_exp_f32_e32 v92, v92
	v_mfma_f32_32x32x16_bf16 v[18:33], v[12:15], v[214:217], v[18:33]
	v_exp_f32_e32 v93, v93
	v_exp_f32_e32 v94, v94
	v_exp_f32_e32 v95, v95
	v_mfma_f32_32x32x16_bf16 v[50:65], v[12:15], v[226:229], v[50:65]
	v_exp_f32_e32 v96, v96
	v_exp_f32_e32 v97, v97
	v_cvt_pk_bf16_f32 v222, v90, v91
	v_cvt_pk_bf16_f32 v223, v92, v93
	v_cvt_pk_bf16_f32 v224, v94, v95
	v_cvt_pk_bf16_f32 v225, v96, v97
	s_nop 1
	v_mfma_f32_32x32x16_bf16 v[34:49], v[222:225], v[164:167], v[34:49]
	v_mfma_f32_32x32x16_bf16 v[18:33], v[222:225], v[218:221], v[18:33]
	v_mfma_f32_32x32x16_bf16 v[50:65], v[222:225], v[226:229], v[50:65]
	s_branch .LBB0_954
